# layer-0 first grid sync now uses the kernel's own XCD-hierarchical barrier instead of cooperative-groups grid.sync; attention loop: trimmed row-max chain, no m0 save/restore around LDS-DMA, C-init spr
# speedup vs baseline: 1.0334x; 1.0090x over previous
; __device__ __forceinline__ void xcd_barrier(const XcdBarrier& b) {
;     asm volatile("s_waitcnt vmcnt(0)" ::: "memory");
;     __syncthreads();
;     if (threadIdx.x == 0) {
;         unsigned* bar = b.bar;
;         __builtin_amdgcn_s_waitcnt(0);
;         unsigned nloc = b.st[0], nx = b.st[1];
;         if (nloc == 0u) { xcd_barrier_complete(bar, b.x, nloc, nx); b.st[0] = nloc; b.st[1] = nx; }
.LBB0_63:
	s_mov_b64 s[12:13], -1
	s_and_b64 vcc, exec, s[10:11]
	s_nop 0
	s_mov_b64 s[12:13], s[90:91]
	s_getreg_b32 s2, hwreg(HW_REG_XCC_ID, 0, 4)
	s_waitcnt vmcnt(0)
	s_waitcnt lgkmcnt(0)
	s_barrier
	s_mov_b64 s[10:11], exec
	v_readlane_b32 s4, v253, 2
	v_readlane_b32 s5, v253, 3
	s_and_b64 s[4:5], s[10:11], s[4:5]
	s_mov_b64 exec, s[4:5]
	s_cbranch_execz .LBB0_116
	v_readlane_b32 s3, v254, 43
	s_load_dwordx2 s[12:13], s[12:13], 0x88
	s_waitcnt vmcnt(0) expcnt(0) lgkmcnt(0)
	v_mov_b32_e32 v0, s3
	ds_read_b32 v3, v0
	v_readlane_b32 s3, v254, 44
	s_and_b32 s2, s2, 15
	s_waitcnt lgkmcnt(0)
	v_cmp_ne_u32_e32 vcc, 0, v3
	v_mov_b32_e32 v0, s3
	ds_read_b32 v2, v0
	s_cbranch_vccnz .LBB0_80
	s_add_u32 s14, s12, 0x1000
	s_addc_u32 s15, s13, 0
	s_add_u32 s16, s12, 0x1100
	s_addc_u32 s17, s13, 0
	s_add_u32 s18, s12, 0x1200
	s_addc_u32 s19, s13, 0
	s_add_u32 s20, s12, 0x1300
	s_addc_u32 s21, s13, 0
	s_mov_b32 s3, 1
	s_branch .LBB0_68

; #define ATT_DMA_K(j) do { const char* ks_ = (const char*)((j) == 0 ? Kmh : Kbh + (size_t)((j) - 1) * 8192); \
;             _Pragma("unroll") for (int i_ = 0; i_ < 2; ++i_) glds16(ks_ + i_ * 8192 + wid * 1024 + lane * 16, (unsigned)__builtin_amdgcn_readfirstlane(ldsb + ((j) & 3) * 16384 + i_ * 8192 + wid * 1024)); } while (0)
; #define ATT_DMA_V(j) do { const char* vs_ = (const char*)((j) == 0 ? Vmh : Vbh + (size_t)((j) - 1) * 8192); \
;             _Pragma("unroll") for (int i_ = 0; i_ < 2; ++i_) glds16(vs_ + i_ * 8192 + wid * 1024 + lane * 16, (unsigned)__builtin_amdgcn_readfirstlane(ldsb + 65536 + ((j) & 3) * 16384 + i_ * 8192 + wid * 1024)); } while (0)
; __device__ __forceinline__ void attn_phase(LAS unsigned char* lds, const bf16_t* Q, const bf16_t* Kimg, const bf16_t* Vimg, const bf16_t* Kmeta, const bf16_t* Vmeta,
;                                            bf16_t* O, const float* lamp, const float* sublnw, float lambda_init, int G) {
;     ...
;                 if (j + 3 < NT) ATT_DMA_K(j + 3);
;                 if (j + 2 < NT) ATT_DMA_V(j + 2);
.LBB0_754:
	s_mov_b64 s[10:11], 0xe70c000
	v_lshl_add_u64 v[4:5], v[2:3], 0, s[10:11]
	s_mov_b64 s[10:11], 0xe70e000
	v_lshl_add_u64 v[6:7], v[2:3], 0, s[10:11]
	s_add_i32 s10, s38, 0x10000
	s_and_b32 s10, s10, 0xc000
	s_add_i32 s10, s10, s89
	s_mov_b32 m0, s10
	s_nop 0
	global_load_lds_dwordx4 v[4:5], off
	s_addk_i32 s10, 0x2000
	s_mov_b32 m0, s10
	s_nop 0
	global_load_lds_dwordx4 v[6:7], off
	s_add_i32 s10, s43, 3
	s_cmp_ge_u32 s10, s93
	s_cbranch_scc1 .LBB0_752
.LBB0_755:
	s_mov_b64 s[10:11], 0x12708000
	v_lshl_add_u64 v[4:5], v[2:3], 0, s[10:11]
	s_mov_b64 s[10:11], 0x1270a000
	v_lshl_add_u64 v[2:3], v[2:3], 0, s[10:11]
	s_add_i32 s10, s38, 0xc000
	s_and_b32 s10, s10, 0xc000
	s_add_i32 s10, s10, s8
	s_mov_b32 m0, s10
	s_nop 0
	global_load_lds_dwordx4 v[4:5], off
	s_addk_i32 s10, 0x2000
	s_mov_b32 m0, s10
	s_nop 0
	global_load_lds_dwordx4 v[2:3], off
	s_and_b64 vcc, exec, s[30:31]
	s_add_i32 s43, s43, 1
	s_cbranch_vccnz .LBB0_753

; __device__ __forceinline__ float fexp2(float x) { return __builtin_amdgcn_exp2f(x); }
; __device__ __forceinline__ float max3f(float a, float b, float c) { float r; asm("v_max3_f32 %0, %1, %2, %3" : "=v"(r) : "v"(a), "v"(b), "v"(c)); return r; }
; __device__ __forceinline__ void attn_phase(LAS unsigned char* lds, const bf16_t* Q, const bf16_t* Kimg, const bf16_t* Vimg, const bf16_t* Kmeta, const bf16_t* Vmeta,
;                                            bf16_t* O, const float* lamp, const float* sublnw, float lambda_init, int G) {
;     ...
;                     float mxa = max3f(sA[0], sA[1], sA[2]), mxb = max3f(sB[0], sB[1], sB[2]);
; #pragma unroll
;                     for (int r = 3; r < 15; r += 2) { mxa = max3f(mxa, sA[r], sA[r + 1]); mxb = max3f(mxb, sB[r], sB[r + 1]); }
;                     float mx = max3f(mxa, mxb, sA[15]); mx = fmaxf(mx, sB[15]);
;                     mx = half_max(mx);
;                     alpha = 1.f;
;                     if (__any(mx > 64.f)) { const float d = fmaxf(mx, 0.f); alpha = fexp2(-d); mrun += d;
; #pragma unroll
;                         for (int r = 0; r < 16; ++r) { sA[r] -= d; sB[r] -= d; } }
.LBB0_758:
	s_add_i32 s10, s38, 0x4000
	s_and_b32 s10, s10, 0xc000
	v_add_u32_e32 v234, s10, v220
	ds_read_b128 v[184:187], v234
	ds_read_b128 v[188:191], v234 offset:512
	ds_read_b128 v[202:205], v234 offset:1024
	ds_read_b128 v[246:249], v234 offset:1536
	ds_read_b128 v[196:199], v234 offset:4096
	ds_read_b128 v[222:225], v234 offset:4608
	ds_read_b128 v[226:229], v234 offset:5120
	ds_read_b128 v[230:233], v234 offset:5632
	v_max3_f32 v2, v18, v19, v20
	v_max3_f32 v3, v34, v35, v36
	v_max3_f32 v2, v2, v21, v22
	v_max3_f32 v3, v3, v37, v38
	v_max3_f32 v2, v2, v23, v24
	v_max3_f32 v3, v3, v39, v40
	v_max3_f32 v2, v2, v25, v26
	v_max3_f32 v3, v3, v41, v42
	v_max3_f32 v2, v2, v27, v28
	v_max3_f32 v3, v3, v43, v44
	v_max3_f32 v2, v2, v29, v30
	v_max3_f32 v3, v3, v45, v46
	v_max3_f32 v2, v2, v31, v32
	v_max3_f32 v3, v3, v47, v48
	v_max3_f32 v2, v2, v3, v33
	v_max_f32_e32 v2, v2, v49
	v_mov_b32_e32 v3, v2
	s_nop 1
	v_permlane32_swap_b32_e32 v2, v3
	v_max_f32_e32 v2, v2, v3
	v_cmp_lt_f32_e32 vcc, s45, v2
	s_cbranch_vccz .LBB0_760
	v_max_f32_e32 v2, v2, v2
	v_max_f32_e32 v2, 0, v2
	v_exp_f32_e64 v178, -v2
	v_pk_add_f32 v[18:19], v[18:19], v[2:3] op_sel_hi:[1,0] neg_lo:[0,1] neg_hi:[0,1]
	v_pk_add_f32 v[34:35], v[34:35], v[2:3] op_sel_hi:[1,0] neg_lo:[0,1] neg_hi:[0,1]
	v_pk_add_f32 v[20:21], v[20:21], v[2:3] op_sel_hi:[1,0] neg_lo:[0,1] neg_hi:[0,1]
	v_pk_add_f32 v[36:37], v[36:37], v[2:3] op_sel_hi:[1,0] neg_lo:[0,1] neg_hi:[0,1]
	v_pk_add_f32 v[22:23], v[22:23], v[2:3] op_sel_hi:[1,0] neg_lo:[0,1] neg_hi:[0,1]
	v_pk_add_f32 v[38:39], v[38:39], v[2:3] op_sel_hi:[1,0] neg_lo:[0,1] neg_hi:[0,1]
	v_pk_add_f32 v[24:25], v[24:25], v[2:3] op_sel_hi:[1,0] neg_lo:[0,1] neg_hi:[0,1]
	v_pk_add_f32 v[40:41], v[40:41], v[2:3] op_sel_hi:[1,0] neg_lo:[0,1] neg_hi:[0,1]
	v_pk_add_f32 v[26:27], v[26:27], v[2:3] op_sel_hi:[1,0] neg_lo:[0,1] neg_hi:[0,1]
	v_pk_add_f32 v[42:43], v[42:43], v[2:3] op_sel_hi:[1,0] neg_lo:[0,1] neg_hi:[0,1]
	v_pk_add_f32 v[28:29], v[28:29], v[2:3] op_sel_hi:[1,0] neg_lo:[0,1] neg_hi:[0,1]
	v_pk_add_f32 v[44:45], v[44:45], v[2:3] op_sel_hi:[1,0] neg_lo:[0,1] neg_hi:[0,1]
	v_pk_add_f32 v[30:31], v[30:31], v[2:3] op_sel_hi:[1,0] neg_lo:[0,1] neg_hi:[0,1]
	v_pk_add_f32 v[46:47], v[46:47], v[2:3] op_sel_hi:[1,0] neg_lo:[0,1] neg_hi:[0,1]
	v_pk_add_f32 v[32:33], v[32:33], v[2:3] op_sel_hi:[1,0] neg_lo:[0,1] neg_hi:[0,1]
	v_pk_add_f32 v[48:49], v[48:49], v[2:3] op_sel_hi:[1,0] neg_lo:[0,1] neg_hi:[0,1]
	v_add_f32_e32 v173, v173, v2
	s_branch .LBB0_761

; #define LAS __attribute__((address_space(3)))
; __device__ __forceinline__ unsigned pk_bf16(float lo, float hi) { f32x2_t v = {lo, hi}; bf16x2_t b = __builtin_convertvector(v, bf16x2_t); return __builtin_bit_cast(unsigned, b); }
; __device__ __forceinline__ float fexp2(float x) { return __builtin_amdgcn_exp2f(x); }
; #define SBAR __builtin_amdgcn_sched_barrier(0)
; __device__ __forceinline__ void attn_phase(LAS unsigned char* lds, const bf16_t* Q, const bf16_t* Kimg, const bf16_t* Vimg, const bf16_t* Kmeta, const bf16_t* Vmeta,
;                                            bf16_t* O, const float* lamp, const float* sublnw, float lambda_init, int G) {
;     ...
;                     float ps = 0.f;
; #pragma unroll
;                     for (int q4 = 0; q4 < 8; ++q4) {
;                         const float a0 = fexp2(sA[2 * q4]), a1 = fexp2(sA[2 * q4 + 1]), b0 = fexp2(sB[2 * q4]), b1 = fexp2(sB[2 * q4 + 1]);
;                         ps += (a0 + a1) + (b0 + b1);
;                         pk[q4 >> 2][q4 & 3] = pk_bf16(a0, a1); pk[2 + (q4 >> 2)][q4 & 3] = pk_bf16(b0, b1); }
;                     lrun = lrun * alpha + ps;
;                 }
;                 if (skew == 1) { if (j + 3 < NT) WAITV_BAR(4); else WAITV_BAR(0); }
;                 if (active) {
;                     const LAS unsigned char* Vb = lds + 65536 + (j & 3) * 16384;
;                     const LAS unsigned char* Kb = lds + ((j + 1) & 3) * 16384;
;                     bf16x8 fa[4], fb[4];
;     ...
;                     __builtin_amdgcn_s_setprio(1);
;                     VFR(fa, 0);
;                     if (__any(alpha != 1.f)) {
; #pragma unroll
;                         for (int d = 0; d < 4; ++d)
; #pragma unroll
;                             for (int r = 0; r < 16; ++r) o[d][r] *= alpha;
;                     }
;                     SBAR; VFR(fb, 1); SBAR; PVM(fa, 0); SBAR; VFR(fa, 2); SBAR; PVM(fb, 1); SBAR; VFR(fb, 3); SBAR; PVM(fa, 2); SBAR; KFR(fa, 0); SBAR; PVM(fb, 3); SBAR; KFR(fb, 1);
;                     { const int kp0_ = 16 + 64 * j; const float tb_ = slope2 * (float)(kp0_ - qpos0 + 8 * hi) - mrun;
; #pragma unroll
;                       for (int r = 0; r < 16; ++r) { sA[r] = fmaf(slope2, (float)(16 * (r >> 3) + (r & 7)), tb_); sB[r] = fmaf(slope2, (float)(32 + 16 * (r >> 3) + (r & 7)), tb_); } }
;                     SBAR; QKM(fa, 0); SBAR; QKM(fb, 1);
.Latt_noalpha:
	s_waitcnt lgkmcnt(7)
	v_mfma_f32_32x32x16_bf16 v[98:113], v[184:187], v[138:141], v[98:113]
	v_exp_f32_e32 v3, v26
	v_exp_f32_e32 v5, v27
	s_waitcnt lgkmcnt(6)
	v_mfma_f32_32x32x16_bf16 v[82:97], v[188:191], v[138:141], v[82:97]
	v_exp_f32_e32 v4, v28
	v_exp_f32_e32 v2, v29
	s_waitcnt lgkmcnt(5)
	v_mfma_f32_32x32x16_bf16 v[66:81], v[202:205], v[138:141], v[66:81]
	v_exp_f32_e32 v6, v30
	v_exp_f32_e32 v7, v31
	s_waitcnt lgkmcnt(4)
	v_mfma_f32_32x32x16_bf16 v[50:65], v[246:249], v[138:141], v[50:65]
	v_exp_f32_e32 v8, v32
	v_exp_f32_e32 v9, v33
	ds_read_b128 v[184:187], v234 offset:8192
	ds_read_b128 v[188:191], v234 offset:8704
	ds_read_b128 v[202:205], v234 offset:9216
	ds_read_b128 v[246:249], v234 offset:9728
	v_cvt_pk_bf16_f32 v142, v3, v5
	v_cvt_pk_bf16_f32 v143, v4, v2
	v_cvt_pk_bf16_f32 v144, v6, v7
	v_cvt_pk_bf16_f32 v145, v8, v9
	v_add_f32_e32 v240, v3, v5
	v_add_f32_e32 v241, v4, v2
	v_add_f32_e32 v242, v6, v7
	v_add_f32_e32 v243, v8, v9
	v_cvt_f32_i32_e32 v193, v179
	v_mov_b32_e32 v177, v176
	s_waitcnt lgkmcnt(7)
	v_mfma_f32_32x32x16_bf16 v[98:113], v[196:199], v[142:145], v[98:113]
	v_exp_f32_e32 v3, v34
	v_exp_f32_e32 v5, v35
	v_fma_f32 v193, v176, v193, -v173
	s_waitcnt lgkmcnt(6)
	v_mfma_f32_32x32x16_bf16 v[82:97], v[222:225], v[142:145], v[82:97]
	v_exp_f32_e32 v4, v36
	v_exp_f32_e32 v2, v37
	v_fma_f32 v18, 0, v176, v193
	v_add_f32_e32 v19, v176, v193
	s_waitcnt lgkmcnt(5)
	v_mfma_f32_32x32x16_bf16 v[66:81], v[226:229], v[142:145], v[66:81]
	v_exp_f32_e32 v6, v38
	v_exp_f32_e32 v7, v39
	v_fmamk_f32 v20, v176, 0x40000000, v193
	v_fmamk_f32 v21, v176, 0x40400000, v193
	s_waitcnt lgkmcnt(4)
	v_mfma_f32_32x32x16_bf16 v[50:65], v[230:233], v[142:145], v[50:65]
	v_exp_f32_e32 v8, v40
	v_exp_f32_e32 v9, v41
	v_fmamk_f32 v22, v176, 0x40800000, v193
	v_fmamk_f32 v23, v176, 0x40a00000, v193
	ds_read_b128 v[196:199], v234 offset:12288
	ds_read_b128 v[222:225], v234 offset:12800
	ds_read_b128 v[226:229], v234 offset:13312
	ds_read_b128 v[230:233], v234 offset:13824
	v_cvt_pk_bf16_f32 v134, v3, v5
	v_cvt_pk_bf16_f32 v135, v4, v2
	v_cvt_pk_bf16_f32 v136, v6, v7
	v_cvt_pk_bf16_f32 v137, v8, v9
	v_add_f32_e32 v11, v3, v5
	v_add_f32_e32 v12, v4, v2
	v_add_f32_e32 v13, v6, v7
	v_add_f32_e32 v192, v8, v9
	s_waitcnt lgkmcnt(7)
	v_mfma_f32_32x32x16_bf16 v[98:113], v[184:187], v[134:137], v[98:113]
	v_exp_f32_e32 v3, v42
	v_exp_f32_e32 v5, v43
	v_add_f32_e32 v236, v11, v236
	v_fmamk_f32 v24, v176, 0x40c00000, v193
	v_fmamk_f32 v25, v176, 0x40e00000, v193
	s_waitcnt lgkmcnt(6)
	v_mfma_f32_32x32x16_bf16 v[82:97], v[188:191], v[134:137], v[82:97]
	v_exp_f32_e32 v4, v44
	v_exp_f32_e32 v2, v45
	v_add_f32_e32 v237, v12, v237
	v_fmamk_f32 v26, v176, 0x41800000, v193
	v_fmamk_f32 v27, v176, 0x41880000, v193
	s_waitcnt lgkmcnt(5)
	v_mfma_f32_32x32x16_bf16 v[66:81], v[202:205], v[134:137], v[66:81]
	v_exp_f32_e32 v6, v46
	v_exp_f32_e32 v7, v47
	v_add_f32_e32 v10, v237, v236
	v_add_f32_e32 v238, v13, v238
	v_fmamk_f32 v28, v176, 0x41900000, v193
	v_fmamk_f32 v29, v176, 0x41980000, v193
	s_waitcnt lgkmcnt(4)
	v_mfma_f32_32x32x16_bf16 v[50:65], v[246:249], v[134:137], v[50:65]
	v_exp_f32_e32 v8, v48
	v_exp_f32_e32 v9, v49
	v_add_f32_e32 v239, v192, v239
	v_add_f32_e32 v10, v238, v10
	v_fmamk_f32 v30, v176, 0x41a00000, v193
	v_fmamk_f32 v31, v176, 0x41a80000, v193
	s_add_i32 s10, s38, 0x8000
	s_and_b32 s10, s10, 0xc000
	v_add_u32_e32 v235, s10, v221
	ds_read_b128 v[184:187], v235
	ds_read_b128 v[188:191], v235 offset:512
	ds_read_b128 v[202:205], v235 offset:2048
	ds_read_b128 v[246:249], v235 offset:2560
	v_cvt_pk_bf16_f32 v146, v3, v5
	v_cvt_pk_bf16_f32 v147, v4, v2
	v_cvt_pk_bf16_f32 v148, v6, v7
	v_cvt_pk_bf16_f32 v149, v8, v9
	v_add_f32_e32 v11, v3, v5
	v_add_f32_e32 v12, v4, v2
	v_add_f32_e32 v13, v6, v7
	v_add_f32_e32 v192, v8, v9
	v_add_f32_e32 v10, v239, v10
	s_waitcnt lgkmcnt(7)
	v_mfma_f32_32x32x16_bf16 v[98:113], v[196:199], v[146:149], v[98:113]
	v_add_f32_e32 v240, v11, v240
	v_add_f32_e32 v10, v240, v10
	v_fmamk_f32 v34, v176, 0x42000000, v193
	v_fmamk_f32 v35, v176, 0x42040000, v193
	v_fmamk_f32 v36, v176, 0x42080000, v193
	v_fmamk_f32 v37, v176, 0x420c0000, v193
	s_waitcnt lgkmcnt(6)
	v_mfma_f32_32x32x16_bf16 v[82:97], v[222:225], v[146:149], v[82:97]
	v_add_f32_e32 v241, v12, v241
	v_add_f32_e32 v10, v241, v10
	v_fmamk_f32 v38, v176, 0x42100000, v193
	v_fmamk_f32 v39, v176, 0x42140000, v193
	v_fmamk_f32 v40, v176, 0x42180000, v193
	v_fmamk_f32 v41, v176, 0x421c0000, v193
	s_waitcnt lgkmcnt(5)
	v_mfma_f32_32x32x16_bf16 v[66:81], v[226:229], v[146:149], v[66:81]
	v_add_f32_e32 v242, v13, v242
	v_add_f32_e32 v10, v242, v10
	v_fmamk_f32 v42, v176, 0x42400000, v193
	v_fmamk_f32 v43, v176, 0x42440000, v193
	v_fmamk_f32 v44, v176, 0x42480000, v193
	v_fmamk_f32 v45, v176, 0x424c0000, v193
	s_waitcnt lgkmcnt(4)
	v_mfma_f32_32x32x16_bf16 v[50:65], v[230:233], v[146:149], v[50:65]
	v_add_f32_e32 v243, v192, v243
	v_add_f32_e32 v10, v243, v10
	v_fmamk_f32 v46, v176, 0x42500000, v193
	v_fmamk_f32 v47, v176, 0x42540000, v193
	v_fmamk_f32 v48, v176, 0x42580000, v193
	v_fmamk_f32 v49, v176, 0x425c0000, v193
	v_fma_f32 v17, v17, v178, v10
	v_fmamk_f32 v32, v176, 0x41b00000, v193
	v_fmamk_f32 v33, v176, 0x41b80000, v193
	ds_read_b128 v[196:199], v235 offset:4096
	ds_read_b128 v[222:225], v235 offset:4608
	ds_read_b128 v[226:229], v235 offset:6144
	ds_read_b128 v[230:233], v235 offset:6656
	s_waitcnt lgkmcnt(7)
	v_mfma_f32_32x32x16_bf16 v[18:33], v[184:187], v[118:121], v[18:33]
	s_waitcnt lgkmcnt(6)
	v_mfma_f32_32x32x16_bf16 v[34:49], v[188:191], v[118:121], v[34:49]
	s_waitcnt lgkmcnt(5)
	v_mfma_f32_32x32x16_bf16 v[18:33], v[202:205], v[122:125], v[18:33]
	s_waitcnt lgkmcnt(4)
	v_mfma_f32_32x32x16_bf16 v[34:49], v[246:249], v[122:125], v[34:49]
	s_waitcnt lgkmcnt(3)
	v_mfma_f32_32x32x16_bf16 v[18:33], v[196:199], v[126:129], v[18:33]
	s_waitcnt lgkmcnt(2)
	v_mfma_f32_32x32x16_bf16 v[34:49], v[222:225], v[126:129], v[34:49]
	s_waitcnt lgkmcnt(1)
	v_mfma_f32_32x32x16_bf16 v[18:33], v[226:229], v[130:133], v[18:33]
	s_waitcnt lgkmcnt(0)
	v_mfma_f32_32x32x16_bf16 v[34:49], v[230:233], v[130:133], v[34:49]
	s_setprio 0
